# v13 + per-lane partial row max decides the rare rescale path (cross-lane max only inside the rare path)
# speedup vs baseline: 1.1561x; 1.0004x over previous
.Lat_mainloop:
.Lat_step_M1:
	v_add_u32_e32 v243, s16, v204
	ds_read_b64_tr_b16 v[214:215], v243 offset:24576
	ds_read_b64_tr_b16 v[216:217], v243 offset:25088
	v_mfma_f32_32x32x16_bf16 v[112:127], v[176:179], v[144:147], v[64:79]
	v_add_f32_e32 v245, v80, v81
	v_add_f32_e32 v245, v82, v245
	v_add_f32_e32 v245, v83, v245
	v_add_f32_e32 v245, v84, v245
	v_add_f32_e32 v245, v85, v245
	v_cvt_pk_bf16_f32 v160, v80, v81
	v_cvt_pk_bf16_f32 v161, v82, v83
	ds_read_b64_tr_b16 v[80:81], v243 offset:28672
	ds_read_b64_tr_b16 v[82:83], v243 offset:29184
	v_mfma_f32_32x32x16_bf16 v[128:143], v[180:183], v[144:147], v[64:79]
	v_add_f32_e32 v245, v86, v245
	v_add_f32_e32 v245, v87, v245
	v_add_f32_e32 v245, v88, v245
	v_add_f32_e32 v245, v89, v245
	v_cvt_pk_bf16_f32 v162, v84, v85
	v_cvt_pk_bf16_f32 v163, v86, v87
	ds_read_b64_tr_b16 v[84:85], v243 offset:25600
	ds_read_b64_tr_b16 v[86:87], v243 offset:26112
	v_mfma_f32_32x32x16_bf16 v[112:127], v[184:187], v[148:151], v[112:127]
	v_add_f32_e32 v245, v90, v245
	v_add_f32_e32 v245, v91, v245
	v_add_f32_e32 v245, v92, v245
	v_add_f32_e32 v245, v93, v245
	v_cvt_pk_bf16_f32 v164, v88, v89
	v_cvt_pk_bf16_f32 v165, v90, v91
	ds_read_b64_tr_b16 v[88:89], v243 offset:29696
	ds_read_b64_tr_b16 v[90:91], v243 offset:30208
	v_mfma_f32_32x32x16_bf16 v[128:143], v[188:191], v[148:151], v[128:143]
	v_add_f32_e32 v245, v94, v245
	v_add_f32_e32 v245, v95, v245
	v_add_f32_e32 v245, v96, v245
	v_add_f32_e32 v245, v97, v245
	v_cvt_pk_bf16_f32 v166, v92, v93
	v_cvt_pk_bf16_f32 v167, v94, v95
	ds_read_b64_tr_b16 v[92:93], v243 offset:26624
	ds_read_b64_tr_b16 v[94:95], v243 offset:27136
	v_mfma_f32_32x32x16_bf16 v[112:127], v[192:195], v[152:155], v[112:127]
	v_add_f32_e32 v245, v98, v245
	v_add_f32_e32 v245, v99, v245
	v_add_f32_e32 v245, v100, v245
	v_add_f32_e32 v245, v101, v245
	v_cvt_pk_bf16_f32 v168, v96, v97
	v_cvt_pk_bf16_f32 v169, v98, v99
	ds_read_b64_tr_b16 v[96:97], v243 offset:30720
	ds_read_b64_tr_b16 v[98:99], v243 offset:31232
	v_mfma_f32_32x32x16_bf16 v[128:143], v[196:199], v[152:155], v[128:143]
	v_add_f32_e32 v245, v102, v245
	v_add_f32_e32 v245, v103, v245
	v_add_f32_e32 v245, v104, v245
	v_add_f32_e32 v245, v105, v245
	v_cvt_pk_bf16_f32 v170, v100, v101
	v_cvt_pk_bf16_f32 v171, v102, v103
	ds_read_b64_tr_b16 v[100:101], v243 offset:27648
	ds_read_b64_tr_b16 v[102:103], v243 offset:28160
	v_mfma_f32_32x32x16_bf16 v[112:127], v[200:203], v[156:159], v[112:127]
	v_add_f32_e32 v245, v106, v245
	v_add_f32_e32 v245, v107, v245
	v_add_f32_e32 v245, v108, v245
	v_add_f32_e32 v245, v109, v245
	v_cvt_pk_bf16_f32 v172, v104, v105
	v_cvt_pk_bf16_f32 v173, v106, v107
	ds_read_b64_tr_b16 v[104:105], v243 offset:31744
	ds_read_b64_tr_b16 v[106:107], v243 offset:32256
	v_mfma_f32_32x32x16_bf16 v[128:143], v[206:209], v[156:159], v[128:143]
	v_add_f32_e32 v245, v110, v245
	v_add_f32_e32 v245, v111, v245
	v_cvt_pk_bf16_f32 v174, v108, v109
	v_cvt_pk_bf16_f32 v175, v110, v111
	v_add_f32_e32 v211, v211, v245
	v_add_u32_e32 v244, s18, v219
	s_waitcnt lgkmcnt(8)
	v_mfma_f32_32x32x16_bf16 v[0:15], v[160:163], v[214:217], v[0:15]
	v_max3_f32 v246, v112, v113, v114
	v_max3_f32 v247, v115, v116, v117
	ds_read_b64_tr_b16 v[214:215], v243 offset:49152
	ds_read_b64_tr_b16 v[216:217], v243 offset:49664
	v_mfma_f32_32x32x16_bf16 v[16:31], v[160:163], v[80:83], v[16:31]
	s_add_i32 m0, s17, s54
	v_max3_f32 v246, v246, v118, v119
	v_max3_f32 v247, v247, v120, v121
	v_max3_f32 v246, v246, v122, v123
	v_max3_f32 v247, v247, v124, v125
	ds_read_b64_tr_b16 v[80:81], v243 offset:53248
	ds_read_b64_tr_b16 v[82:83], v243 offset:53760
	global_load_lds_dwordx4 v222, s[0:1]
	s_add_u32 s0, s0, 0x20000
	s_addc_u32 s1, s1, 0
	v_mfma_f32_32x32x16_bf16 v[0:15], v[164:167], v[84:87], v[0:15]
	s_add_i32 s21, s18, s54
	s_add_i32 m0, s21, 0x6000
	v_max3_f32 v246, v246, v126, v127
	v_max3_f32 v247, v247, v128, v129
	v_max3_f32 v246, v246, v130, v131
	v_max3_f32 v247, v247, v132, v133
	ds_read_b64_tr_b16 v[84:85], v243 offset:50176
	ds_read_b64_tr_b16 v[86:87], v243 offset:50688
	global_load_lds_dwordx4 v223, s[4:5]
	v_mfma_f32_32x32x16_bf16 v[16:31], v[164:167], v[88:91], v[16:31]
	s_add_i32 m0, s21, 0xc000
	v_max3_f32 v246, v246, v134, v135
	v_max3_f32 v247, v247, v136, v137
	v_max3_f32 v246, v246, v138, v139
	v_max3_f32 v247, v247, v140, v141
	ds_read_b64_tr_b16 v[88:89], v243 offset:54272
	ds_read_b64_tr_b16 v[90:91], v243 offset:54784
	global_load_lds_dwordx4 v224, s[4:5]
	s_add_u32 s4, s4, 0x20000
	s_addc_u32 s5, s5, 0
	s_waitcnt lgkmcnt(8)
	v_mfma_f32_32x32x16_bf16 v[0:15], v[168:171], v[92:95], v[0:15]
	v_max3_f32 v246, v246, v142, v143
	v_max_f32_e32 v248, v246, v247
	ds_read_b64_tr_b16 v[92:93], v243 offset:51200
	ds_read_b64_tr_b16 v[94:95], v243 offset:51712
	v_cmp_lt_f32_e32 vcc, s87, v248
	s_cbranch_vccnz .Lat_rare_M1

.Lat_step_M2:
	v_add_u32_e32 v243, s16, v204
	ds_read_b64_tr_b16 v[214:215], v243 offset:24576
	ds_read_b64_tr_b16 v[216:217], v243 offset:25088
	v_mfma_f32_32x32x16_bf16 v[80:95], v[176:179], v[144:147], v[64:79]
	v_add_f32_e32 v245, v112, v113
	v_add_f32_e32 v245, v114, v245
	v_add_f32_e32 v245, v115, v245
	v_add_f32_e32 v245, v116, v245
	v_add_f32_e32 v245, v117, v245
	v_cvt_pk_bf16_f32 v160, v112, v113
	v_cvt_pk_bf16_f32 v161, v114, v115
	ds_read_b64_tr_b16 v[112:113], v243 offset:28672
	ds_read_b64_tr_b16 v[114:115], v243 offset:29184
	v_mfma_f32_32x32x16_bf16 v[96:111], v[180:183], v[144:147], v[64:79]
	v_add_f32_e32 v245, v118, v245
	v_add_f32_e32 v245, v119, v245
	v_add_f32_e32 v245, v120, v245
	v_add_f32_e32 v245, v121, v245
	v_cvt_pk_bf16_f32 v162, v116, v117
	v_cvt_pk_bf16_f32 v163, v118, v119
	ds_read_b64_tr_b16 v[116:117], v243 offset:25600
	ds_read_b64_tr_b16 v[118:119], v243 offset:26112
	v_mfma_f32_32x32x16_bf16 v[80:95], v[184:187], v[148:151], v[80:95]
	v_add_f32_e32 v245, v122, v245
	v_add_f32_e32 v245, v123, v245
	v_add_f32_e32 v245, v124, v245
	v_add_f32_e32 v245, v125, v245
	v_cvt_pk_bf16_f32 v164, v120, v121
	v_cvt_pk_bf16_f32 v165, v122, v123
	ds_read_b64_tr_b16 v[120:121], v243 offset:29696
	ds_read_b64_tr_b16 v[122:123], v243 offset:30208
	v_mfma_f32_32x32x16_bf16 v[96:111], v[188:191], v[148:151], v[96:111]
	v_add_f32_e32 v245, v126, v245
	v_add_f32_e32 v245, v127, v245
	v_add_f32_e32 v245, v128, v245
	v_add_f32_e32 v245, v129, v245
	v_cvt_pk_bf16_f32 v166, v124, v125
	v_cvt_pk_bf16_f32 v167, v126, v127
	ds_read_b64_tr_b16 v[124:125], v243 offset:26624
	ds_read_b64_tr_b16 v[126:127], v243 offset:27136
	v_mfma_f32_32x32x16_bf16 v[80:95], v[192:195], v[152:155], v[80:95]
	v_add_f32_e32 v245, v130, v245
	v_add_f32_e32 v245, v131, v245
	v_add_f32_e32 v245, v132, v245
	v_add_f32_e32 v245, v133, v245
	v_cvt_pk_bf16_f32 v168, v128, v129
	v_cvt_pk_bf16_f32 v169, v130, v131
	ds_read_b64_tr_b16 v[128:129], v243 offset:30720
	ds_read_b64_tr_b16 v[130:131], v243 offset:31232
	v_mfma_f32_32x32x16_bf16 v[96:111], v[196:199], v[152:155], v[96:111]
	v_add_f32_e32 v245, v134, v245
	v_add_f32_e32 v245, v135, v245
	v_add_f32_e32 v245, v136, v245
	v_add_f32_e32 v245, v137, v245
	v_cvt_pk_bf16_f32 v170, v132, v133
	v_cvt_pk_bf16_f32 v171, v134, v135
	ds_read_b64_tr_b16 v[132:133], v243 offset:27648
	ds_read_b64_tr_b16 v[134:135], v243 offset:28160
	v_mfma_f32_32x32x16_bf16 v[80:95], v[200:203], v[156:159], v[80:95]
	v_add_f32_e32 v245, v138, v245
	v_add_f32_e32 v245, v139, v245
	v_add_f32_e32 v245, v140, v245
	v_add_f32_e32 v245, v141, v245
	v_cvt_pk_bf16_f32 v172, v136, v137
	v_cvt_pk_bf16_f32 v173, v138, v139
	ds_read_b64_tr_b16 v[136:137], v243 offset:31744
	ds_read_b64_tr_b16 v[138:139], v243 offset:32256
	v_mfma_f32_32x32x16_bf16 v[96:111], v[206:209], v[156:159], v[96:111]
	v_add_f32_e32 v245, v142, v245
	v_add_f32_e32 v245, v143, v245
	v_cvt_pk_bf16_f32 v174, v140, v141
	v_cvt_pk_bf16_f32 v175, v142, v143
	v_add_f32_e32 v211, v211, v245
	v_add_u32_e32 v244, s18, v219
	s_waitcnt lgkmcnt(8)
	v_mfma_f32_32x32x16_bf16 v[0:15], v[160:163], v[214:217], v[0:15]
	v_max3_f32 v246, v80, v81, v82
	v_max3_f32 v247, v83, v84, v85
	ds_read_b64_tr_b16 v[214:215], v243 offset:49152
	ds_read_b64_tr_b16 v[216:217], v243 offset:49664
	v_mfma_f32_32x32x16_bf16 v[16:31], v[160:163], v[112:115], v[16:31]
	s_add_i32 m0, s17, s54
	v_max3_f32 v246, v246, v86, v87
	v_max3_f32 v247, v247, v88, v89
	v_max3_f32 v246, v246, v90, v91
	v_max3_f32 v247, v247, v92, v93
	ds_read_b64_tr_b16 v[112:113], v243 offset:53248
	ds_read_b64_tr_b16 v[114:115], v243 offset:53760
	global_load_lds_dwordx4 v222, s[0:1]
	s_add_u32 s0, s0, 0x20000
	s_addc_u32 s1, s1, 0
	v_mfma_f32_32x32x16_bf16 v[0:15], v[164:167], v[116:119], v[0:15]
	s_add_i32 s21, s18, s54
	s_add_i32 m0, s21, 0x6000
	v_max3_f32 v246, v246, v94, v95
	v_max3_f32 v247, v247, v96, v97
	v_max3_f32 v246, v246, v98, v99
	v_max3_f32 v247, v247, v100, v101
	ds_read_b64_tr_b16 v[116:117], v243 offset:50176
	ds_read_b64_tr_b16 v[118:119], v243 offset:50688
	global_load_lds_dwordx4 v223, s[4:5]
	v_mfma_f32_32x32x16_bf16 v[16:31], v[164:167], v[120:123], v[16:31]
	s_add_i32 m0, s21, 0xc000
	v_max3_f32 v246, v246, v102, v103
	v_max3_f32 v247, v247, v104, v105
	v_max3_f32 v246, v246, v106, v107
	v_max3_f32 v247, v247, v108, v109
	ds_read_b64_tr_b16 v[120:121], v243 offset:54272
	ds_read_b64_tr_b16 v[122:123], v243 offset:54784
	global_load_lds_dwordx4 v224, s[4:5]
	s_add_u32 s4, s4, 0x20000
	s_addc_u32 s5, s5, 0
	s_waitcnt lgkmcnt(8)
	v_mfma_f32_32x32x16_bf16 v[0:15], v[168:171], v[124:127], v[0:15]
	v_max3_f32 v246, v246, v110, v111
	v_max_f32_e32 v248, v246, v247
	ds_read_b64_tr_b16 v[124:125], v243 offset:51200
	ds_read_b64_tr_b16 v[126:127], v243 offset:51712
	v_cmp_lt_f32_e32 vcc, s87, v248
	s_cbranch_vccnz .Lat_rare_M2

.Lat_step_T5:
	v_add_u32_e32 v243, s16, v204
	ds_read_b64_tr_b16 v[214:215], v243 offset:24576
	ds_read_b64_tr_b16 v[216:217], v243 offset:25088
	v_mfma_f32_32x32x16_bf16 v[112:127], v[176:179], v[144:147], v[64:79]
	v_add_f32_e32 v245, v80, v81
	v_add_f32_e32 v245, v82, v245
	v_add_f32_e32 v245, v83, v245
	v_add_f32_e32 v245, v84, v245
	v_add_f32_e32 v245, v85, v245
	v_cvt_pk_bf16_f32 v160, v80, v81
	v_cvt_pk_bf16_f32 v161, v82, v83
	ds_read_b64_tr_b16 v[80:81], v243 offset:28672
	ds_read_b64_tr_b16 v[82:83], v243 offset:29184
	v_mfma_f32_32x32x16_bf16 v[128:143], v[180:183], v[144:147], v[64:79]
	v_add_f32_e32 v245, v86, v245
	v_add_f32_e32 v245, v87, v245
	v_add_f32_e32 v245, v88, v245
	v_add_f32_e32 v245, v89, v245
	v_cvt_pk_bf16_f32 v162, v84, v85
	v_cvt_pk_bf16_f32 v163, v86, v87
	ds_read_b64_tr_b16 v[84:85], v243 offset:25600
	ds_read_b64_tr_b16 v[86:87], v243 offset:26112
	v_mfma_f32_32x32x16_bf16 v[112:127], v[184:187], v[148:151], v[112:127]
	v_add_f32_e32 v245, v90, v245
	v_add_f32_e32 v245, v91, v245
	v_add_f32_e32 v245, v92, v245
	v_add_f32_e32 v245, v93, v245
	v_cvt_pk_bf16_f32 v164, v88, v89
	v_cvt_pk_bf16_f32 v165, v90, v91
	ds_read_b64_tr_b16 v[88:89], v243 offset:29696
	ds_read_b64_tr_b16 v[90:91], v243 offset:30208
	v_mfma_f32_32x32x16_bf16 v[128:143], v[188:191], v[148:151], v[128:143]
	v_add_f32_e32 v245, v94, v245
	v_add_f32_e32 v245, v95, v245
	v_add_f32_e32 v245, v96, v245
	v_add_f32_e32 v245, v97, v245
	v_cvt_pk_bf16_f32 v166, v92, v93
	v_cvt_pk_bf16_f32 v167, v94, v95
	ds_read_b64_tr_b16 v[92:93], v243 offset:26624
	ds_read_b64_tr_b16 v[94:95], v243 offset:27136
	v_mfma_f32_32x32x16_bf16 v[112:127], v[192:195], v[152:155], v[112:127]
	v_add_f32_e32 v245, v98, v245
	v_add_f32_e32 v245, v99, v245
	v_add_f32_e32 v245, v100, v245
	v_add_f32_e32 v245, v101, v245
	v_cvt_pk_bf16_f32 v168, v96, v97
	v_cvt_pk_bf16_f32 v169, v98, v99
	ds_read_b64_tr_b16 v[96:97], v243 offset:30720
	ds_read_b64_tr_b16 v[98:99], v243 offset:31232
	v_mfma_f32_32x32x16_bf16 v[128:143], v[196:199], v[152:155], v[128:143]
	v_add_f32_e32 v245, v102, v245
	v_add_f32_e32 v245, v103, v245
	v_add_f32_e32 v245, v104, v245
	v_add_f32_e32 v245, v105, v245
	v_cvt_pk_bf16_f32 v170, v100, v101
	v_cvt_pk_bf16_f32 v171, v102, v103
	ds_read_b64_tr_b16 v[100:101], v243 offset:27648
	ds_read_b64_tr_b16 v[102:103], v243 offset:28160
	v_mfma_f32_32x32x16_bf16 v[112:127], v[200:203], v[156:159], v[112:127]
	v_add_f32_e32 v245, v106, v245
	v_add_f32_e32 v245, v107, v245
	v_add_f32_e32 v245, v108, v245
	v_add_f32_e32 v245, v109, v245
	v_cvt_pk_bf16_f32 v172, v104, v105
	v_cvt_pk_bf16_f32 v173, v106, v107
	ds_read_b64_tr_b16 v[104:105], v243 offset:31744
	ds_read_b64_tr_b16 v[106:107], v243 offset:32256
	v_mfma_f32_32x32x16_bf16 v[128:143], v[206:209], v[156:159], v[128:143]
	v_add_f32_e32 v245, v110, v245
	v_add_f32_e32 v245, v111, v245
	v_cvt_pk_bf16_f32 v174, v108, v109
	v_cvt_pk_bf16_f32 v175, v110, v111
	v_add_f32_e32 v211, v211, v245
	v_add_u32_e32 v244, s18, v219
	s_waitcnt lgkmcnt(8)
	v_mfma_f32_32x32x16_bf16 v[0:15], v[160:163], v[214:217], v[0:15]
	v_max3_f32 v246, v112, v113, v114
	v_max3_f32 v247, v115, v116, v117
	ds_read_b64_tr_b16 v[214:215], v243 offset:49152
	ds_read_b64_tr_b16 v[216:217], v243 offset:49664
	v_mfma_f32_32x32x16_bf16 v[16:31], v[160:163], v[80:83], v[16:31]
	s_add_i32 m0, s17, s54
	v_max3_f32 v246, v246, v118, v119
	v_max3_f32 v247, v247, v120, v121
	v_max3_f32 v246, v246, v122, v123
	v_max3_f32 v247, v247, v124, v125
	ds_read_b64_tr_b16 v[80:81], v243 offset:53248
	ds_read_b64_tr_b16 v[82:83], v243 offset:53760
	global_load_lds_dwordx4 v222, s[0:1]
	s_add_u32 s0, s0, 0x20000
	s_addc_u32 s1, s1, 0
	v_mfma_f32_32x32x16_bf16 v[0:15], v[164:167], v[84:87], v[0:15]
	s_add_i32 s21, s18, s54
	s_add_i32 m0, s21, 0x6000
	v_max3_f32 v246, v246, v126, v127
	v_max3_f32 v247, v247, v128, v129
	v_max3_f32 v246, v246, v130, v131
	v_max3_f32 v247, v247, v132, v133
	ds_read_b64_tr_b16 v[84:85], v243 offset:50176
	ds_read_b64_tr_b16 v[86:87], v243 offset:50688
	global_load_lds_dwordx4 v223, s[4:5]
	v_mfma_f32_32x32x16_bf16 v[16:31], v[164:167], v[88:91], v[16:31]
	s_add_i32 m0, s21, 0xc000
	v_max3_f32 v246, v246, v134, v135
	v_max3_f32 v247, v247, v136, v137
	v_max3_f32 v246, v246, v138, v139
	v_max3_f32 v247, v247, v140, v141
	ds_read_b64_tr_b16 v[88:89], v243 offset:54272
	ds_read_b64_tr_b16 v[90:91], v243 offset:54784
	global_load_lds_dwordx4 v224, s[4:5]
	s_add_u32 s4, s4, 0x20000
	s_addc_u32 s5, s5, 0
	s_waitcnt lgkmcnt(8)
	v_mfma_f32_32x32x16_bf16 v[0:15], v[168:171], v[92:95], v[0:15]
	v_max3_f32 v246, v246, v142, v143
	v_max_f32_e32 v248, v246, v247
	ds_read_b64_tr_b16 v[92:93], v243 offset:51200
	ds_read_b64_tr_b16 v[94:95], v243 offset:51712
	v_cmp_lt_f32_e32 vcc, s87, v248
	s_cbranch_vccnz .Lat_rare_T5

.Lat_step_T4:
	v_add_u32_e32 v243, s16, v204
	ds_read_b64_tr_b16 v[214:215], v243 offset:24576
	ds_read_b64_tr_b16 v[216:217], v243 offset:25088
	v_mfma_f32_32x32x16_bf16 v[80:95], v[176:179], v[144:147], v[64:79]
	v_add_f32_e32 v245, v112, v113
	v_add_f32_e32 v245, v114, v245
	v_add_f32_e32 v245, v115, v245
	v_add_f32_e32 v245, v116, v245
	v_add_f32_e32 v245, v117, v245
	v_cvt_pk_bf16_f32 v160, v112, v113
	v_cvt_pk_bf16_f32 v161, v114, v115
	ds_read_b64_tr_b16 v[112:113], v243 offset:28672
	ds_read_b64_tr_b16 v[114:115], v243 offset:29184
	v_mfma_f32_32x32x16_bf16 v[96:111], v[180:183], v[144:147], v[64:79]
	v_add_f32_e32 v245, v118, v245
	v_add_f32_e32 v245, v119, v245
	v_add_f32_e32 v245, v120, v245
	v_add_f32_e32 v245, v121, v245
	v_cvt_pk_bf16_f32 v162, v116, v117
	v_cvt_pk_bf16_f32 v163, v118, v119
	ds_read_b64_tr_b16 v[116:117], v243 offset:25600
	ds_read_b64_tr_b16 v[118:119], v243 offset:26112
	v_mfma_f32_32x32x16_bf16 v[80:95], v[184:187], v[148:151], v[80:95]
	v_add_f32_e32 v245, v122, v245
	v_add_f32_e32 v245, v123, v245
	v_add_f32_e32 v245, v124, v245
	v_add_f32_e32 v245, v125, v245
	v_cvt_pk_bf16_f32 v164, v120, v121
	v_cvt_pk_bf16_f32 v165, v122, v123
	ds_read_b64_tr_b16 v[120:121], v243 offset:29696
	ds_read_b64_tr_b16 v[122:123], v243 offset:30208
	v_mfma_f32_32x32x16_bf16 v[96:111], v[188:191], v[148:151], v[96:111]
	v_add_f32_e32 v245, v126, v245
	v_add_f32_e32 v245, v127, v245
	v_add_f32_e32 v245, v128, v245
	v_add_f32_e32 v245, v129, v245
	v_cvt_pk_bf16_f32 v166, v124, v125
	v_cvt_pk_bf16_f32 v167, v126, v127
	ds_read_b64_tr_b16 v[124:125], v243 offset:26624
	ds_read_b64_tr_b16 v[126:127], v243 offset:27136
	v_mfma_f32_32x32x16_bf16 v[80:95], v[192:195], v[152:155], v[80:95]
	v_add_f32_e32 v245, v130, v245
	v_add_f32_e32 v245, v131, v245
	v_add_f32_e32 v245, v132, v245
	v_add_f32_e32 v245, v133, v245
	v_cvt_pk_bf16_f32 v168, v128, v129
	v_cvt_pk_bf16_f32 v169, v130, v131
	ds_read_b64_tr_b16 v[128:129], v243 offset:30720
	ds_read_b64_tr_b16 v[130:131], v243 offset:31232
	v_mfma_f32_32x32x16_bf16 v[96:111], v[196:199], v[152:155], v[96:111]
	v_add_f32_e32 v245, v134, v245
	v_add_f32_e32 v245, v135, v245
	v_add_f32_e32 v245, v136, v245
	v_add_f32_e32 v245, v137, v245
	v_cvt_pk_bf16_f32 v170, v132, v133
	v_cvt_pk_bf16_f32 v171, v134, v135
	ds_read_b64_tr_b16 v[132:133], v243 offset:27648
	ds_read_b64_tr_b16 v[134:135], v243 offset:28160
	v_mfma_f32_32x32x16_bf16 v[80:95], v[200:203], v[156:159], v[80:95]
	v_add_f32_e32 v245, v138, v245
	v_add_f32_e32 v245, v139, v245
	v_add_f32_e32 v245, v140, v245
	v_add_f32_e32 v245, v141, v245
	v_cvt_pk_bf16_f32 v172, v136, v137
	v_cvt_pk_bf16_f32 v173, v138, v139
	ds_read_b64_tr_b16 v[136:137], v243 offset:31744
	ds_read_b64_tr_b16 v[138:139], v243 offset:32256
	v_mfma_f32_32x32x16_bf16 v[96:111], v[206:209], v[156:159], v[96:111]
	v_add_f32_e32 v245, v142, v245
	v_add_f32_e32 v245, v143, v245
	v_cvt_pk_bf16_f32 v174, v140, v141
	v_cvt_pk_bf16_f32 v175, v142, v143
	v_add_f32_e32 v211, v211, v245
	v_add_u32_e32 v244, s18, v219
	s_waitcnt lgkmcnt(8)
; __device__ __forceinline__ void cmask(f32x16&p0,f32x16&p1,int jb,int qrel,int hi){
;   const float NEG=-INFINITY; int kb=64*jb+4*hi;
;   #pragma unroll
;   for(int r=0;r<16;++r){int kv=kb+(r&3)+8*(r>>2); if(kv>qrel)p0[r]=NEG; if(kv+32>qrel)p1[r]=NEG;}
; }
	v_mfma_f32_32x32x16_bf16 v[0:15], v[160:163], v[214:217], v[0:15]
	v_cmp_gt_i32_e64 s[28:29], 0, v225
	v_cmp_gt_i32_e64 s[30:31], 1, v225
	v_cmp_gt_i32_e64 s[34:35], 2, v225
	v_cndmask_b32_e64 v80, v80, v241, s[28:29]
	v_cmp_gt_i32_e64 s[28:29], 3, v225
	v_cndmask_b32_e64 v81, v81, v241, s[30:31]
	v_cmp_gt_i32_e64 s[30:31], 8, v225
	v_cndmask_b32_e64 v82, v82, v241, s[34:35]
	v_cmp_gt_i32_e64 s[34:35], 9, v225
	v_cndmask_b32_e64 v83, v83, v241, s[28:29]
	ds_read_b64_tr_b16 v[214:215], v243 offset:49152
	ds_read_b64_tr_b16 v[216:217], v243 offset:49664
	v_mfma_f32_32x32x16_bf16 v[16:31], v[160:163], v[112:115], v[16:31]
	s_add_i32 m0, s17, s54
	v_cmp_gt_i32_e64 s[28:29], 10, v225
	v_cndmask_b32_e64 v84, v84, v241, s[30:31]
	v_cmp_gt_i32_e64 s[30:31], 11, v225
	v_cndmask_b32_e64 v85, v85, v241, s[34:35]
	v_cmp_gt_i32_e64 s[34:35], 16, v225
	v_cndmask_b32_e64 v86, v86, v241, s[28:29]
	v_cmp_gt_i32_e64 s[28:29], 17, v225
	v_cndmask_b32_e64 v87, v87, v241, s[30:31]
	v_cmp_gt_i32_e64 s[30:31], 18, v225
	v_cndmask_b32_e64 v88, v88, v241, s[34:35]
	ds_read_b64_tr_b16 v[112:113], v243 offset:53248
	ds_read_b64_tr_b16 v[114:115], v243 offset:53760
	global_load_lds_dwordx4 v222, s[0:1]
	s_add_u32 s0, s0, 0x20000
	s_addc_u32 s1, s1, 0
	v_mfma_f32_32x32x16_bf16 v[0:15], v[164:167], v[116:119], v[0:15]
	s_add_i32 s21, s18, s54
	s_add_i32 m0, s21, 0x6000
	v_cmp_gt_i32_e64 s[34:35], 19, v225
	v_cndmask_b32_e64 v89, v89, v241, s[28:29]
	v_cmp_gt_i32_e64 s[28:29], 24, v225
	v_cndmask_b32_e64 v90, v90, v241, s[30:31]
	v_cmp_gt_i32_e64 s[30:31], 25, v225
	v_cndmask_b32_e64 v91, v91, v241, s[34:35]
	v_cmp_gt_i32_e64 s[34:35], 26, v225
	v_cndmask_b32_e64 v92, v92, v241, s[28:29]
	v_cmp_gt_i32_e64 s[28:29], 27, v225
	v_cndmask_b32_e64 v93, v93, v241, s[30:31]
	ds_read_b64_tr_b16 v[116:117], v243 offset:50176
	ds_read_b64_tr_b16 v[118:119], v243 offset:50688
	global_load_lds_dwordx4 v223, s[4:5]
	v_mfma_f32_32x32x16_bf16 v[16:31], v[164:167], v[120:123], v[16:31]
	s_add_i32 m0, s21, 0xc000
	v_cmp_gt_i32_e64 s[30:31], 32, v225
	v_cndmask_b32_e64 v94, v94, v241, s[34:35]
	v_cmp_gt_i32_e64 s[34:35], 33, v225
	v_cndmask_b32_e64 v95, v95, v241, s[28:29]
	v_cmp_gt_i32_e64 s[28:29], 34, v225
	v_cndmask_b32_e64 v96, v96, v241, s[30:31]
	v_cmp_gt_i32_e64 s[30:31], 35, v225
	v_cndmask_b32_e64 v97, v97, v241, s[34:35]
	v_cmp_gt_i32_e64 s[34:35], 40, v225
	v_cndmask_b32_e64 v98, v98, v241, s[28:29]
	ds_read_b64_tr_b16 v[120:121], v243 offset:54272
	ds_read_b64_tr_b16 v[122:123], v243 offset:54784
	global_load_lds_dwordx4 v224, s[4:5]
	s_add_u32 s4, s4, 0x20000
	s_addc_u32 s5, s5, 0
	s_waitcnt lgkmcnt(8)
	v_mfma_f32_32x32x16_bf16 v[0:15], v[168:171], v[124:127], v[0:15]
	v_cmp_gt_i32_e64 s[28:29], 41, v225
	v_cndmask_b32_e64 v99, v99, v241, s[30:31]
	v_cmp_gt_i32_e64 s[30:31], 42, v225
	v_cndmask_b32_e64 v100, v100, v241, s[34:35]
	v_cmp_gt_i32_e64 s[34:35], 43, v225
	v_cndmask_b32_e64 v101, v101, v241, s[28:29]
	v_cmp_gt_i32_e64 s[28:29], 48, v225
	v_cndmask_b32_e64 v102, v102, v241, s[30:31]
	v_cmp_gt_i32_e64 s[30:31], 49, v225
	v_cndmask_b32_e64 v103, v103, v241, s[34:35]
	ds_read_b64_tr_b16 v[124:125], v243 offset:51200
	ds_read_b64_tr_b16 v[126:127], v243 offset:51712
	v_mfma_f32_32x32x16_bf16 v[16:31], v[168:171], v[128:131], v[16:31]
	v_cmp_gt_i32_e64 s[34:35], 50, v225
	v_cndmask_b32_e64 v104, v104, v241, s[28:29]
	v_cmp_gt_i32_e64 s[28:29], 51, v225
	v_cndmask_b32_e64 v105, v105, v241, s[30:31]
	v_cmp_gt_i32_e64 s[30:31], 56, v225
	v_cndmask_b32_e64 v106, v106, v241, s[34:35]
	v_cmp_gt_i32_e64 s[34:35], 57, v225
	v_cndmask_b32_e64 v107, v107, v241, s[28:29]
	v_cmp_gt_i32_e64 s[28:29], 58, v225
	v_cndmask_b32_e64 v108, v108, v241, s[30:31]
	ds_read_b64_tr_b16 v[128:129], v243 offset:55296
	ds_read_b64_tr_b16 v[130:131], v243 offset:55808
	v_mfma_f32_32x32x16_bf16 v[0:15], v[172:175], v[132:135], v[0:15]
	v_cmp_gt_i32_e64 s[30:31], 59, v225
	v_cndmask_b32_e64 v109, v109, v241, s[34:35]
	v_cndmask_b32_e64 v110, v110, v241, s[28:29]
	v_cndmask_b32_e64 v111, v111, v241, s[30:31]
	v_max3_f32 v246, v80, v81, v82
	v_max3_f32 v247, v83, v84, v85
	v_max3_f32 v246, v246, v86, v87
	v_max3_f32 v247, v247, v88, v89
	v_max3_f32 v246, v246, v90, v91
	v_max3_f32 v247, v247, v92, v93
	ds_read_b64_tr_b16 v[132:133], v243 offset:52224
	ds_read_b64_tr_b16 v[134:135], v243 offset:52736
	v_mfma_f32_32x32x16_bf16 v[16:31], v[172:175], v[136:139], v[16:31]
	v_max3_f32 v246, v246, v94, v95
	v_max3_f32 v247, v247, v96, v97
	v_max3_f32 v246, v246, v98, v99
	v_max3_f32 v247, v247, v100, v101
	v_max3_f32 v246, v246, v102, v103
	v_max3_f32 v247, v247, v104, v105
	v_max3_f32 v246, v246, v106, v107
	v_max3_f32 v247, v247, v108, v109
	v_max3_f32 v246, v246, v110, v111
	v_max_f32_e32 v248, v246, v247
	ds_read_b64_tr_b16 v[136:137], v243 offset:56320
	ds_read_b64_tr_b16 v[138:139], v243 offset:56832
	s_waitcnt lgkmcnt(8)
	v_mfma_f32_32x32x16_bf16 v[32:47], v[160:163], v[214:217], v[32:47]
	ds_read_b128 v[176:179], v244 offset:0
	ds_read_b128 v[180:183], v244 offset:512
	v_cmp_lt_f32_e32 vcc, s87, v248
	s_cbranch_vccnz .Lat_rare_T4

.Lat_step_T3:
	s_cmp_lt_u32 s55, 1
	s_cbranch_scc1 .Lat_T3_light
	v_add_u32_e32 v243, s16, v204
	ds_read_b64_tr_b16 v[214:215], v243 offset:24576
	ds_read_b64_tr_b16 v[216:217], v243 offset:25088
	v_mfma_f32_32x32x16_bf16 v[112:127], v[176:179], v[144:147], v[64:79]
	v_add_f32_e32 v245, v80, v81
	v_add_f32_e32 v245, v82, v245
	v_add_f32_e32 v245, v83, v245
	v_add_f32_e32 v245, v84, v245
	v_add_f32_e32 v245, v85, v245
	v_cvt_pk_bf16_f32 v160, v80, v81
	v_cvt_pk_bf16_f32 v161, v82, v83
	ds_read_b64_tr_b16 v[80:81], v243 offset:28672
	ds_read_b64_tr_b16 v[82:83], v243 offset:29184
	v_mfma_f32_32x32x16_bf16 v[128:143], v[180:183], v[144:147], v[64:79]
	v_add_f32_e32 v245, v86, v245
	v_add_f32_e32 v245, v87, v245
	v_add_f32_e32 v245, v88, v245
	v_add_f32_e32 v245, v89, v245
	v_cvt_pk_bf16_f32 v162, v84, v85
	v_cvt_pk_bf16_f32 v163, v86, v87
	ds_read_b64_tr_b16 v[84:85], v243 offset:25600
	ds_read_b64_tr_b16 v[86:87], v243 offset:26112
	v_mfma_f32_32x32x16_bf16 v[112:127], v[184:187], v[148:151], v[112:127]
	v_add_f32_e32 v245, v90, v245
	v_add_f32_e32 v245, v91, v245
	v_add_f32_e32 v245, v92, v245
	v_add_f32_e32 v245, v93, v245
	v_cvt_pk_bf16_f32 v164, v88, v89
	v_cvt_pk_bf16_f32 v165, v90, v91
	ds_read_b64_tr_b16 v[88:89], v243 offset:29696
	ds_read_b64_tr_b16 v[90:91], v243 offset:30208
	v_mfma_f32_32x32x16_bf16 v[128:143], v[188:191], v[148:151], v[128:143]
	v_add_f32_e32 v245, v94, v245
	v_add_f32_e32 v245, v95, v245
	v_add_f32_e32 v245, v96, v245
	v_add_f32_e32 v245, v97, v245
	v_cvt_pk_bf16_f32 v166, v92, v93
	v_cvt_pk_bf16_f32 v167, v94, v95
	ds_read_b64_tr_b16 v[92:93], v243 offset:26624
	ds_read_b64_tr_b16 v[94:95], v243 offset:27136
	v_mfma_f32_32x32x16_bf16 v[112:127], v[192:195], v[152:155], v[112:127]
	v_add_f32_e32 v245, v98, v245
	v_add_f32_e32 v245, v99, v245
	v_add_f32_e32 v245, v100, v245
	v_add_f32_e32 v245, v101, v245
	v_cvt_pk_bf16_f32 v168, v96, v97
	v_cvt_pk_bf16_f32 v169, v98, v99
	ds_read_b64_tr_b16 v[96:97], v243 offset:30720
	ds_read_b64_tr_b16 v[98:99], v243 offset:31232
	v_mfma_f32_32x32x16_bf16 v[128:143], v[196:199], v[152:155], v[128:143]
	v_add_f32_e32 v245, v102, v245
	v_add_f32_e32 v245, v103, v245
	v_add_f32_e32 v245, v104, v245
	v_add_f32_e32 v245, v105, v245
	v_cvt_pk_bf16_f32 v170, v100, v101
	v_cvt_pk_bf16_f32 v171, v102, v103
	ds_read_b64_tr_b16 v[100:101], v243 offset:27648
	ds_read_b64_tr_b16 v[102:103], v243 offset:28160
	v_mfma_f32_32x32x16_bf16 v[112:127], v[200:203], v[156:159], v[112:127]
	v_add_f32_e32 v245, v106, v245
	v_add_f32_e32 v245, v107, v245
	v_add_f32_e32 v245, v108, v245
	v_add_f32_e32 v245, v109, v245
	v_cvt_pk_bf16_f32 v172, v104, v105
	v_cvt_pk_bf16_f32 v173, v106, v107
	ds_read_b64_tr_b16 v[104:105], v243 offset:31744
	ds_read_b64_tr_b16 v[106:107], v243 offset:32256
	v_mfma_f32_32x32x16_bf16 v[128:143], v[206:209], v[156:159], v[128:143]
	v_add_f32_e32 v245, v110, v245
	v_add_f32_e32 v245, v111, v245
	v_cvt_pk_bf16_f32 v174, v108, v109
	v_cvt_pk_bf16_f32 v175, v110, v111
	v_add_f32_e32 v211, v211, v245
	v_add_u32_e32 v244, s18, v219
	s_waitcnt lgkmcnt(8)
; __device__ __forceinline__ void cmask(f32x16&p0,f32x16&p1,int jb,int qrel,int hi){
;   const float NEG=-INFINITY; int kb=64*jb+4*hi;
;   #pragma unroll
;   for(int r=0;r<16;++r){int kv=kb+(r&3)+8*(r>>2); if(kv>qrel)p0[r]=NEG; if(kv+32>qrel)p1[r]=NEG;}
; }
	v_mfma_f32_32x32x16_bf16 v[0:15], v[160:163], v[214:217], v[0:15]
	v_add_u32_e32 v242, 0xffffffc0, v225
	v_cmp_gt_i32_e64 s[28:29], 0, v242
	v_cmp_gt_i32_e64 s[30:31], 1, v242
	v_cmp_gt_i32_e64 s[34:35], 2, v242
	v_cndmask_b32_e64 v112, v112, v241, s[28:29]
	v_cmp_gt_i32_e64 s[28:29], 3, v242
	v_cndmask_b32_e64 v113, v113, v241, s[30:31]
	v_cmp_gt_i32_e64 s[30:31], 8, v242
	v_cndmask_b32_e64 v114, v114, v241, s[34:35]
	v_cmp_gt_i32_e64 s[34:35], 9, v242
	ds_read_b64_tr_b16 v[214:215], v243 offset:49152
	ds_read_b64_tr_b16 v[216:217], v243 offset:49664
	v_mfma_f32_32x32x16_bf16 v[16:31], v[160:163], v[80:83], v[16:31]
	v_cndmask_b32_e64 v115, v115, v241, s[28:29]
	v_cmp_gt_i32_e64 s[28:29], 10, v242
	v_cndmask_b32_e64 v116, v116, v241, s[30:31]
	v_cmp_gt_i32_e64 s[30:31], 11, v242
	v_cndmask_b32_e64 v117, v117, v241, s[34:35]
	v_cmp_gt_i32_e64 s[34:35], 16, v242
	v_cndmask_b32_e64 v118, v118, v241, s[28:29]
	v_cmp_gt_i32_e64 s[28:29], 17, v242
	v_cndmask_b32_e64 v119, v119, v241, s[30:31]
	v_cmp_gt_i32_e64 s[30:31], 18, v242
	ds_read_b64_tr_b16 v[80:81], v243 offset:53248
	ds_read_b64_tr_b16 v[82:83], v243 offset:53760
	v_mfma_f32_32x32x16_bf16 v[0:15], v[164:167], v[84:87], v[0:15]
	s_add_i32 s21, s18, s54
	s_add_i32 m0, s21, 0x6000
	v_cndmask_b32_e64 v120, v120, v241, s[34:35]
	v_cmp_gt_i32_e64 s[34:35], 19, v242
	v_cndmask_b32_e64 v121, v121, v241, s[28:29]
	v_cmp_gt_i32_e64 s[28:29], 24, v242
	v_cndmask_b32_e64 v122, v122, v241, s[30:31]
	v_cmp_gt_i32_e64 s[30:31], 25, v242
	v_cndmask_b32_e64 v123, v123, v241, s[34:35]
	v_cmp_gt_i32_e64 s[34:35], 26, v242
	v_cndmask_b32_e64 v124, v124, v241, s[28:29]
	v_cmp_gt_i32_e64 s[28:29], 27, v242
	ds_read_b64_tr_b16 v[84:85], v243 offset:50176
	ds_read_b64_tr_b16 v[86:87], v243 offset:50688
	global_load_lds_dwordx4 v223, s[4:5]
	v_mfma_f32_32x32x16_bf16 v[16:31], v[164:167], v[88:91], v[16:31]
	s_add_i32 m0, s21, 0xc000
	v_cndmask_b32_e64 v125, v125, v241, s[30:31]
	v_cmp_gt_i32_e64 s[30:31], 32, v242
	v_cndmask_b32_e64 v126, v126, v241, s[34:35]
	v_cmp_gt_i32_e64 s[34:35], 33, v242
	v_cndmask_b32_e64 v127, v127, v241, s[28:29]
	v_cmp_gt_i32_e64 s[28:29], 34, v242
	v_cndmask_b32_e64 v128, v128, v241, s[30:31]
	v_cmp_gt_i32_e64 s[30:31], 35, v242
	v_cndmask_b32_e64 v129, v129, v241, s[34:35]
	v_cmp_gt_i32_e64 s[34:35], 40, v242
	ds_read_b64_tr_b16 v[88:89], v243 offset:54272
	ds_read_b64_tr_b16 v[90:91], v243 offset:54784
	global_load_lds_dwordx4 v224, s[4:5]
	s_add_u32 s4, s4, 0x20000
	s_addc_u32 s5, s5, 0
	s_waitcnt lgkmcnt(8)
	v_mfma_f32_32x32x16_bf16 v[0:15], v[168:171], v[92:95], v[0:15]
	v_cndmask_b32_e64 v130, v130, v241, s[28:29]
	v_cmp_gt_i32_e64 s[28:29], 41, v242
	v_cndmask_b32_e64 v131, v131, v241, s[30:31]
	v_cmp_gt_i32_e64 s[30:31], 42, v242
	v_cndmask_b32_e64 v132, v132, v241, s[34:35]
	v_cmp_gt_i32_e64 s[34:35], 43, v242
	v_cndmask_b32_e64 v133, v133, v241, s[28:29]
	v_cmp_gt_i32_e64 s[28:29], 48, v242
	v_cndmask_b32_e64 v134, v134, v241, s[30:31]
	v_cmp_gt_i32_e64 s[30:31], 49, v242
	ds_read_b64_tr_b16 v[92:93], v243 offset:51200
	ds_read_b64_tr_b16 v[94:95], v243 offset:51712
	v_mfma_f32_32x32x16_bf16 v[16:31], v[168:171], v[96:99], v[16:31]
	v_cndmask_b32_e64 v135, v135, v241, s[34:35]
	v_cmp_gt_i32_e64 s[34:35], 50, v242
	v_cndmask_b32_e64 v136, v136, v241, s[28:29]
	v_cmp_gt_i32_e64 s[28:29], 51, v242
	v_cndmask_b32_e64 v137, v137, v241, s[30:31]
	v_cmp_gt_i32_e64 s[30:31], 56, v242
	v_cndmask_b32_e64 v138, v138, v241, s[34:35]
	v_cmp_gt_i32_e64 s[34:35], 57, v242
	v_cndmask_b32_e64 v139, v139, v241, s[28:29]
	v_cmp_gt_i32_e64 s[28:29], 58, v242
	ds_read_b64_tr_b16 v[96:97], v243 offset:55296
	ds_read_b64_tr_b16 v[98:99], v243 offset:55808
	v_mfma_f32_32x32x16_bf16 v[0:15], v[172:175], v[100:103], v[0:15]
	v_cndmask_b32_e64 v140, v140, v241, s[30:31]
	v_cmp_gt_i32_e64 s[30:31], 59, v242
	v_cndmask_b32_e64 v141, v141, v241, s[34:35]
	v_cndmask_b32_e64 v142, v142, v241, s[28:29]
	v_cndmask_b32_e64 v143, v143, v241, s[30:31]
	v_max3_f32 v246, v112, v113, v114
	v_max3_f32 v247, v115, v116, v117
	v_max3_f32 v246, v246, v118, v119
	v_max3_f32 v247, v247, v120, v121
	v_max3_f32 v246, v246, v122, v123
	ds_read_b64_tr_b16 v[100:101], v243 offset:52224
	ds_read_b64_tr_b16 v[102:103], v243 offset:52736
	v_mfma_f32_32x32x16_bf16 v[16:31], v[172:175], v[104:107], v[16:31]
	v_max3_f32 v247, v247, v124, v125
	v_max3_f32 v246, v246, v126, v127
	v_max3_f32 v247, v247, v128, v129
	v_max3_f32 v246, v246, v130, v131
	v_max3_f32 v247, v247, v132, v133
	v_max3_f32 v246, v246, v134, v135
	v_max3_f32 v247, v247, v136, v137
	v_max3_f32 v246, v246, v138, v139
	v_max3_f32 v247, v247, v140, v141
	v_max3_f32 v246, v246, v142, v143
	ds_read_b64_tr_b16 v[104:105], v243 offset:56320
	ds_read_b64_tr_b16 v[106:107], v243 offset:56832
	s_waitcnt lgkmcnt(8)
	v_mfma_f32_32x32x16_bf16 v[32:47], v[160:163], v[214:217], v[32:47]
	v_max_f32_e32 v248, v246, v247
	ds_read_b128 v[176:179], v244 offset:0
	ds_read_b128 v[180:183], v244 offset:512
	v_cmp_lt_f32_e32 vcc, s87, v248
	s_cbranch_vccnz .Lat_rare_T3

.Lat_T3_end:
.Lat_step_T2:
	s_cmp_lt_u32 s55, 2
	s_cbranch_scc1 .Lat_T2_light
	v_add_u32_e32 v243, s16, v204
	ds_read_b64_tr_b16 v[214:215], v243 offset:24576
	ds_read_b64_tr_b16 v[216:217], v243 offset:25088
	v_mfma_f32_32x32x16_bf16 v[80:95], v[176:179], v[144:147], v[64:79]
	v_add_f32_e32 v245, v112, v113
	v_add_f32_e32 v245, v114, v245
	v_add_f32_e32 v245, v115, v245
	v_add_f32_e32 v245, v116, v245
	v_add_f32_e32 v245, v117, v245
	v_cvt_pk_bf16_f32 v160, v112, v113
	v_cvt_pk_bf16_f32 v161, v114, v115
	ds_read_b64_tr_b16 v[112:113], v243 offset:28672
	ds_read_b64_tr_b16 v[114:115], v243 offset:29184
	v_mfma_f32_32x32x16_bf16 v[96:111], v[180:183], v[144:147], v[64:79]
	v_add_f32_e32 v245, v118, v245
	v_add_f32_e32 v245, v119, v245
	v_add_f32_e32 v245, v120, v245
	v_add_f32_e32 v245, v121, v245
	v_cvt_pk_bf16_f32 v162, v116, v117
	v_cvt_pk_bf16_f32 v163, v118, v119
	ds_read_b64_tr_b16 v[116:117], v243 offset:25600
	ds_read_b64_tr_b16 v[118:119], v243 offset:26112
	v_mfma_f32_32x32x16_bf16 v[80:95], v[184:187], v[148:151], v[80:95]
	v_add_f32_e32 v245, v122, v245
	v_add_f32_e32 v245, v123, v245
	v_add_f32_e32 v245, v124, v245
	v_add_f32_e32 v245, v125, v245
	v_cvt_pk_bf16_f32 v164, v120, v121
	v_cvt_pk_bf16_f32 v165, v122, v123
	ds_read_b64_tr_b16 v[120:121], v243 offset:29696
	ds_read_b64_tr_b16 v[122:123], v243 offset:30208
	v_mfma_f32_32x32x16_bf16 v[96:111], v[188:191], v[148:151], v[96:111]
	v_add_f32_e32 v245, v126, v245
	v_add_f32_e32 v245, v127, v245
	v_add_f32_e32 v245, v128, v245
	v_add_f32_e32 v245, v129, v245
	v_cvt_pk_bf16_f32 v166, v124, v125
	v_cvt_pk_bf16_f32 v167, v126, v127
	ds_read_b64_tr_b16 v[124:125], v243 offset:26624
	ds_read_b64_tr_b16 v[126:127], v243 offset:27136
	v_mfma_f32_32x32x16_bf16 v[80:95], v[192:195], v[152:155], v[80:95]
	v_add_f32_e32 v245, v130, v245
	v_add_f32_e32 v245, v131, v245
	v_add_f32_e32 v245, v132, v245
	v_add_f32_e32 v245, v133, v245
	v_cvt_pk_bf16_f32 v168, v128, v129
	v_cvt_pk_bf16_f32 v169, v130, v131
	ds_read_b64_tr_b16 v[128:129], v243 offset:30720
	ds_read_b64_tr_b16 v[130:131], v243 offset:31232
	v_mfma_f32_32x32x16_bf16 v[96:111], v[196:199], v[152:155], v[96:111]
	v_add_f32_e32 v245, v134, v245
	v_add_f32_e32 v245, v135, v245
	v_add_f32_e32 v245, v136, v245
	v_add_f32_e32 v245, v137, v245
	v_cvt_pk_bf16_f32 v170, v132, v133
	v_cvt_pk_bf16_f32 v171, v134, v135
	ds_read_b64_tr_b16 v[132:133], v243 offset:27648
	ds_read_b64_tr_b16 v[134:135], v243 offset:28160
	v_mfma_f32_32x32x16_bf16 v[80:95], v[200:203], v[156:159], v[80:95]
	v_add_f32_e32 v245, v138, v245
	v_add_f32_e32 v245, v139, v245
	v_add_f32_e32 v245, v140, v245
	v_add_f32_e32 v245, v141, v245
	v_cvt_pk_bf16_f32 v172, v136, v137
	v_cvt_pk_bf16_f32 v173, v138, v139
	ds_read_b64_tr_b16 v[136:137], v243 offset:31744
	ds_read_b64_tr_b16 v[138:139], v243 offset:32256
	v_mfma_f32_32x32x16_bf16 v[96:111], v[206:209], v[156:159], v[96:111]
	v_add_f32_e32 v245, v142, v245
	v_add_f32_e32 v245, v143, v245
	v_cvt_pk_bf16_f32 v174, v140, v141
	v_cvt_pk_bf16_f32 v175, v142, v143
	v_add_f32_e32 v211, v211, v245
	v_add_u32_e32 v244, s18, v219
	s_waitcnt lgkmcnt(8)
; __device__ __forceinline__ void cmask(f32x16&p0,f32x16&p1,int jb,int qrel,int hi){
;   const float NEG=-INFINITY; int kb=64*jb+4*hi;
;   #pragma unroll
;   for(int r=0;r<16;++r){int kv=kb+(r&3)+8*(r>>2); if(kv>qrel)p0[r]=NEG; if(kv+32>qrel)p1[r]=NEG;}
; }
	v_mfma_f32_32x32x16_bf16 v[0:15], v[160:163], v[214:217], v[0:15]
	v_add_u32_e32 v242, 0xffffff80, v225
	v_cmp_gt_i32_e64 s[28:29], 0, v242
	v_cmp_gt_i32_e64 s[30:31], 1, v242
	v_cmp_gt_i32_e64 s[34:35], 2, v242
	v_cndmask_b32_e64 v80, v80, v241, s[28:29]
	v_cmp_gt_i32_e64 s[28:29], 3, v242
	v_cndmask_b32_e64 v81, v81, v241, s[30:31]
	v_cmp_gt_i32_e64 s[30:31], 8, v242
	v_cndmask_b32_e64 v82, v82, v241, s[34:35]
	v_cmp_gt_i32_e64 s[34:35], 9, v242
	ds_read_b64_tr_b16 v[214:215], v243 offset:49152
	ds_read_b64_tr_b16 v[216:217], v243 offset:49664
	v_mfma_f32_32x32x16_bf16 v[16:31], v[160:163], v[112:115], v[16:31]
	v_cndmask_b32_e64 v83, v83, v241, s[28:29]
	v_cmp_gt_i32_e64 s[28:29], 10, v242
	v_cndmask_b32_e64 v84, v84, v241, s[30:31]
	v_cmp_gt_i32_e64 s[30:31], 11, v242
	v_cndmask_b32_e64 v85, v85, v241, s[34:35]
	v_cmp_gt_i32_e64 s[34:35], 16, v242
	v_cndmask_b32_e64 v86, v86, v241, s[28:29]
	v_cmp_gt_i32_e64 s[28:29], 17, v242
	v_cndmask_b32_e64 v87, v87, v241, s[30:31]
	v_cmp_gt_i32_e64 s[30:31], 18, v242
	ds_read_b64_tr_b16 v[112:113], v243 offset:53248
	ds_read_b64_tr_b16 v[114:115], v243 offset:53760
	v_mfma_f32_32x32x16_bf16 v[0:15], v[164:167], v[116:119], v[0:15]
	s_add_i32 s21, s18, s54
	s_add_i32 m0, s21, 0x6000
	v_cndmask_b32_e64 v88, v88, v241, s[34:35]
	v_cmp_gt_i32_e64 s[34:35], 19, v242
	v_cndmask_b32_e64 v89, v89, v241, s[28:29]
	v_cmp_gt_i32_e64 s[28:29], 24, v242
	v_cndmask_b32_e64 v90, v90, v241, s[30:31]
	v_cmp_gt_i32_e64 s[30:31], 25, v242
	v_cndmask_b32_e64 v91, v91, v241, s[34:35]
	v_cmp_gt_i32_e64 s[34:35], 26, v242
	v_cndmask_b32_e64 v92, v92, v241, s[28:29]
	v_cmp_gt_i32_e64 s[28:29], 27, v242
	ds_read_b64_tr_b16 v[116:117], v243 offset:50176
	ds_read_b64_tr_b16 v[118:119], v243 offset:50688
	global_load_lds_dwordx4 v223, s[4:5]
	v_mfma_f32_32x32x16_bf16 v[16:31], v[164:167], v[120:123], v[16:31]
	s_add_i32 m0, s21, 0xc000
	v_cndmask_b32_e64 v93, v93, v241, s[30:31]
	v_cmp_gt_i32_e64 s[30:31], 32, v242
	v_cndmask_b32_e64 v94, v94, v241, s[34:35]
	v_cmp_gt_i32_e64 s[34:35], 33, v242
	v_cndmask_b32_e64 v95, v95, v241, s[28:29]
	v_cmp_gt_i32_e64 s[28:29], 34, v242
	v_cndmask_b32_e64 v96, v96, v241, s[30:31]
	v_cmp_gt_i32_e64 s[30:31], 35, v242
	v_cndmask_b32_e64 v97, v97, v241, s[34:35]
	v_cmp_gt_i32_e64 s[34:35], 40, v242
	ds_read_b64_tr_b16 v[120:121], v243 offset:54272
	ds_read_b64_tr_b16 v[122:123], v243 offset:54784
	global_load_lds_dwordx4 v224, s[4:5]
	s_add_u32 s4, s4, 0x20000
	s_addc_u32 s5, s5, 0
	s_waitcnt lgkmcnt(8)
	v_mfma_f32_32x32x16_bf16 v[0:15], v[168:171], v[124:127], v[0:15]
	v_cndmask_b32_e64 v98, v98, v241, s[28:29]
	v_cmp_gt_i32_e64 s[28:29], 41, v242
	v_cndmask_b32_e64 v99, v99, v241, s[30:31]
	v_cmp_gt_i32_e64 s[30:31], 42, v242
	v_cndmask_b32_e64 v100, v100, v241, s[34:35]
	v_cmp_gt_i32_e64 s[34:35], 43, v242
	v_cndmask_b32_e64 v101, v101, v241, s[28:29]
	v_cmp_gt_i32_e64 s[28:29], 48, v242
	v_cndmask_b32_e64 v102, v102, v241, s[30:31]
	v_cmp_gt_i32_e64 s[30:31], 49, v242
	ds_read_b64_tr_b16 v[124:125], v243 offset:51200
	ds_read_b64_tr_b16 v[126:127], v243 offset:51712
	v_mfma_f32_32x32x16_bf16 v[16:31], v[168:171], v[128:131], v[16:31]
	v_cndmask_b32_e64 v103, v103, v241, s[34:35]
	v_cmp_gt_i32_e64 s[34:35], 50, v242
	v_cndmask_b32_e64 v104, v104, v241, s[28:29]
	v_cmp_gt_i32_e64 s[28:29], 51, v242
	v_cndmask_b32_e64 v105, v105, v241, s[30:31]
	v_cmp_gt_i32_e64 s[30:31], 56, v242
	v_cndmask_b32_e64 v106, v106, v241, s[34:35]
	v_cmp_gt_i32_e64 s[34:35], 57, v242
	v_cndmask_b32_e64 v107, v107, v241, s[28:29]
	v_cmp_gt_i32_e64 s[28:29], 58, v242
	ds_read_b64_tr_b16 v[128:129], v243 offset:55296
	ds_read_b64_tr_b16 v[130:131], v243 offset:55808
	v_mfma_f32_32x32x16_bf16 v[0:15], v[172:175], v[132:135], v[0:15]
	v_cndmask_b32_e64 v108, v108, v241, s[30:31]
	v_cmp_gt_i32_e64 s[30:31], 59, v242
	v_cndmask_b32_e64 v109, v109, v241, s[34:35]
	v_cndmask_b32_e64 v110, v110, v241, s[28:29]
	v_cndmask_b32_e64 v111, v111, v241, s[30:31]
	v_max3_f32 v246, v80, v81, v82
	v_max3_f32 v247, v83, v84, v85
	v_max3_f32 v246, v246, v86, v87
	v_max3_f32 v247, v247, v88, v89
	v_max3_f32 v246, v246, v90, v91
	ds_read_b64_tr_b16 v[132:133], v243 offset:52224
	ds_read_b64_tr_b16 v[134:135], v243 offset:52736
	v_mfma_f32_32x32x16_bf16 v[16:31], v[172:175], v[136:139], v[16:31]
	v_max3_f32 v247, v247, v92, v93
	v_max3_f32 v246, v246, v94, v95
	v_max3_f32 v247, v247, v96, v97
	v_max3_f32 v246, v246, v98, v99
	v_max3_f32 v247, v247, v100, v101
	v_max3_f32 v246, v246, v102, v103
	v_max3_f32 v247, v247, v104, v105
	v_max3_f32 v246, v246, v106, v107
	v_max3_f32 v247, v247, v108, v109
	v_max3_f32 v246, v246, v110, v111
	ds_read_b64_tr_b16 v[136:137], v243 offset:56320
	ds_read_b64_tr_b16 v[138:139], v243 offset:56832
	s_waitcnt lgkmcnt(8)
	v_mfma_f32_32x32x16_bf16 v[32:47], v[160:163], v[214:217], v[32:47]
	v_max_f32_e32 v248, v246, v247
	ds_read_b128 v[176:179], v244 offset:0
	ds_read_b128 v[180:183], v244 offset:512
	v_cmp_lt_f32_e32 vcc, s87, v248
	s_cbranch_vccnz .Lat_rare_T2

.Lat_T2_end:
.Lat_step_T1:
	s_cmp_lt_u32 s55, 3
	s_cbranch_scc1 .Lat_T1_light
	v_add_u32_e32 v243, s16, v204
	ds_read_b64_tr_b16 v[214:215], v243 offset:24576
	ds_read_b64_tr_b16 v[216:217], v243 offset:25088
	v_mfma_f32_32x32x16_bf16 v[112:127], v[176:179], v[144:147], v[64:79]
	v_add_f32_e32 v245, v80, v81
	v_add_f32_e32 v245, v82, v245
	v_add_f32_e32 v245, v83, v245
	v_add_f32_e32 v245, v84, v245
	v_add_f32_e32 v245, v85, v245
	v_cvt_pk_bf16_f32 v160, v80, v81
	v_cvt_pk_bf16_f32 v161, v82, v83
	ds_read_b64_tr_b16 v[80:81], v243 offset:28672
	ds_read_b64_tr_b16 v[82:83], v243 offset:29184
	v_mfma_f32_32x32x16_bf16 v[128:143], v[180:183], v[144:147], v[64:79]
	v_add_f32_e32 v245, v86, v245
	v_add_f32_e32 v245, v87, v245
	v_add_f32_e32 v245, v88, v245
	v_add_f32_e32 v245, v89, v245
	v_cvt_pk_bf16_f32 v162, v84, v85
	v_cvt_pk_bf16_f32 v163, v86, v87
	ds_read_b64_tr_b16 v[84:85], v243 offset:25600
	ds_read_b64_tr_b16 v[86:87], v243 offset:26112
	v_mfma_f32_32x32x16_bf16 v[112:127], v[184:187], v[148:151], v[112:127]
	v_add_f32_e32 v245, v90, v245
	v_add_f32_e32 v245, v91, v245
	v_add_f32_e32 v245, v92, v245
	v_add_f32_e32 v245, v93, v245
	v_cvt_pk_bf16_f32 v164, v88, v89
	v_cvt_pk_bf16_f32 v165, v90, v91
	ds_read_b64_tr_b16 v[88:89], v243 offset:29696
	ds_read_b64_tr_b16 v[90:91], v243 offset:30208
	v_mfma_f32_32x32x16_bf16 v[128:143], v[188:191], v[148:151], v[128:143]
	v_add_f32_e32 v245, v94, v245
	v_add_f32_e32 v245, v95, v245
	v_add_f32_e32 v245, v96, v245
	v_add_f32_e32 v245, v97, v245
	v_cvt_pk_bf16_f32 v166, v92, v93
	v_cvt_pk_bf16_f32 v167, v94, v95
	ds_read_b64_tr_b16 v[92:93], v243 offset:26624
	ds_read_b64_tr_b16 v[94:95], v243 offset:27136
	v_mfma_f32_32x32x16_bf16 v[112:127], v[192:195], v[152:155], v[112:127]
	v_add_f32_e32 v245, v98, v245
	v_add_f32_e32 v245, v99, v245
	v_add_f32_e32 v245, v100, v245
	v_add_f32_e32 v245, v101, v245
	v_cvt_pk_bf16_f32 v168, v96, v97
	v_cvt_pk_bf16_f32 v169, v98, v99
	ds_read_b64_tr_b16 v[96:97], v243 offset:30720
	ds_read_b64_tr_b16 v[98:99], v243 offset:31232
	v_mfma_f32_32x32x16_bf16 v[128:143], v[196:199], v[152:155], v[128:143]
	v_add_f32_e32 v245, v102, v245
	v_add_f32_e32 v245, v103, v245
	v_add_f32_e32 v245, v104, v245
	v_add_f32_e32 v245, v105, v245
	v_cvt_pk_bf16_f32 v170, v100, v101
	v_cvt_pk_bf16_f32 v171, v102, v103
	ds_read_b64_tr_b16 v[100:101], v243 offset:27648
	ds_read_b64_tr_b16 v[102:103], v243 offset:28160
	v_mfma_f32_32x32x16_bf16 v[112:127], v[200:203], v[156:159], v[112:127]
	v_add_f32_e32 v245, v106, v245
	v_add_f32_e32 v245, v107, v245
	v_add_f32_e32 v245, v108, v245
	v_add_f32_e32 v245, v109, v245
	v_cvt_pk_bf16_f32 v172, v104, v105
	v_cvt_pk_bf16_f32 v173, v106, v107
	ds_read_b64_tr_b16 v[104:105], v243 offset:31744
	ds_read_b64_tr_b16 v[106:107], v243 offset:32256
	v_mfma_f32_32x32x16_bf16 v[128:143], v[206:209], v[156:159], v[128:143]
	v_add_f32_e32 v245, v110, v245
	v_add_f32_e32 v245, v111, v245
	v_cvt_pk_bf16_f32 v174, v108, v109
	v_cvt_pk_bf16_f32 v175, v110, v111
	v_add_f32_e32 v211, v211, v245
	s_waitcnt lgkmcnt(8)
; __device__ __forceinline__ void cmask(f32x16&p0,f32x16&p1,int jb,int qrel,int hi){
;   const float NEG=-INFINITY; int kb=64*jb+4*hi;
;   #pragma unroll
;   for(int r=0;r<16;++r){int kv=kb+(r&3)+8*(r>>2); if(kv>qrel)p0[r]=NEG; if(kv+32>qrel)p1[r]=NEG;}
; }
	v_mfma_f32_32x32x16_bf16 v[0:15], v[160:163], v[214:217], v[0:15]
	v_add_u32_e32 v242, 0xffffff40, v225
	v_cmp_gt_i32_e64 s[28:29], 0, v242
	v_cmp_gt_i32_e64 s[30:31], 1, v242
	v_cmp_gt_i32_e64 s[34:35], 2, v242
	v_cndmask_b32_e64 v112, v112, v241, s[28:29]
	v_cmp_gt_i32_e64 s[28:29], 3, v242
	v_cndmask_b32_e64 v113, v113, v241, s[30:31]
	v_cmp_gt_i32_e64 s[30:31], 8, v242
	v_cndmask_b32_e64 v114, v114, v241, s[34:35]
	v_cmp_gt_i32_e64 s[34:35], 9, v242
	ds_read_b64_tr_b16 v[214:215], v243 offset:49152
	ds_read_b64_tr_b16 v[216:217], v243 offset:49664
	v_mfma_f32_32x32x16_bf16 v[16:31], v[160:163], v[80:83], v[16:31]
	v_cndmask_b32_e64 v115, v115, v241, s[28:29]
	v_cmp_gt_i32_e64 s[28:29], 10, v242
	v_cndmask_b32_e64 v116, v116, v241, s[30:31]
	v_cmp_gt_i32_e64 s[30:31], 11, v242
	v_cndmask_b32_e64 v117, v117, v241, s[34:35]
	v_cmp_gt_i32_e64 s[34:35], 16, v242
	v_cndmask_b32_e64 v118, v118, v241, s[28:29]
	v_cmp_gt_i32_e64 s[28:29], 17, v242
	v_cndmask_b32_e64 v119, v119, v241, s[30:31]
	v_cmp_gt_i32_e64 s[30:31], 18, v242
	ds_read_b64_tr_b16 v[80:81], v243 offset:53248
	ds_read_b64_tr_b16 v[82:83], v243 offset:53760
	v_mfma_f32_32x32x16_bf16 v[0:15], v[164:167], v[84:87], v[0:15]
	v_cndmask_b32_e64 v120, v120, v241, s[34:35]
	v_cmp_gt_i32_e64 s[34:35], 19, v242
	v_cndmask_b32_e64 v121, v121, v241, s[28:29]
	v_cmp_gt_i32_e64 s[28:29], 24, v242
	v_cndmask_b32_e64 v122, v122, v241, s[30:31]
	v_cmp_gt_i32_e64 s[30:31], 25, v242
	v_cndmask_b32_e64 v123, v123, v241, s[34:35]
	v_cmp_gt_i32_e64 s[34:35], 26, v242
	v_cndmask_b32_e64 v124, v124, v241, s[28:29]
	v_cmp_gt_i32_e64 s[28:29], 27, v242
	ds_read_b64_tr_b16 v[84:85], v243 offset:50176
	ds_read_b64_tr_b16 v[86:87], v243 offset:50688
	v_mfma_f32_32x32x16_bf16 v[16:31], v[164:167], v[88:91], v[16:31]
	v_cndmask_b32_e64 v125, v125, v241, s[30:31]
	v_cmp_gt_i32_e64 s[30:31], 32, v242
	v_cndmask_b32_e64 v126, v126, v241, s[34:35]
	v_cmp_gt_i32_e64 s[34:35], 33, v242
	v_cndmask_b32_e64 v127, v127, v241, s[28:29]
	v_cmp_gt_i32_e64 s[28:29], 34, v242
	v_cndmask_b32_e64 v128, v128, v241, s[30:31]
	v_cmp_gt_i32_e64 s[30:31], 35, v242
	v_cndmask_b32_e64 v129, v129, v241, s[34:35]
	v_cmp_gt_i32_e64 s[34:35], 40, v242
	ds_read_b64_tr_b16 v[88:89], v243 offset:54272
	ds_read_b64_tr_b16 v[90:91], v243 offset:54784
	s_waitcnt lgkmcnt(8)
	v_mfma_f32_32x32x16_bf16 v[0:15], v[168:171], v[92:95], v[0:15]
	v_cndmask_b32_e64 v130, v130, v241, s[28:29]
	v_cmp_gt_i32_e64 s[28:29], 41, v242
	v_cndmask_b32_e64 v131, v131, v241, s[30:31]
	v_cmp_gt_i32_e64 s[30:31], 42, v242
	v_cndmask_b32_e64 v132, v132, v241, s[34:35]
	v_cmp_gt_i32_e64 s[34:35], 43, v242
	v_cndmask_b32_e64 v133, v133, v241, s[28:29]
	v_cmp_gt_i32_e64 s[28:29], 48, v242
	v_cndmask_b32_e64 v134, v134, v241, s[30:31]
	v_cmp_gt_i32_e64 s[30:31], 49, v242
	ds_read_b64_tr_b16 v[92:93], v243 offset:51200
	ds_read_b64_tr_b16 v[94:95], v243 offset:51712
	v_mfma_f32_32x32x16_bf16 v[16:31], v[168:171], v[96:99], v[16:31]
	v_cndmask_b32_e64 v135, v135, v241, s[34:35]
	v_cmp_gt_i32_e64 s[34:35], 50, v242
	v_cndmask_b32_e64 v136, v136, v241, s[28:29]
	v_cmp_gt_i32_e64 s[28:29], 51, v242
	v_cndmask_b32_e64 v137, v137, v241, s[30:31]
	v_cmp_gt_i32_e64 s[30:31], 56, v242
	v_cndmask_b32_e64 v138, v138, v241, s[34:35]
	v_cmp_gt_i32_e64 s[34:35], 57, v242
	v_cndmask_b32_e64 v139, v139, v241, s[28:29]
	v_cmp_gt_i32_e64 s[28:29], 58, v242
	ds_read_b64_tr_b16 v[96:97], v243 offset:55296
	ds_read_b64_tr_b16 v[98:99], v243 offset:55808
	v_mfma_f32_32x32x16_bf16 v[0:15], v[172:175], v[100:103], v[0:15]
	v_cndmask_b32_e64 v140, v140, v241, s[30:31]
	v_cmp_gt_i32_e64 s[30:31], 59, v242
	v_cndmask_b32_e64 v141, v141, v241, s[34:35]
	v_cndmask_b32_e64 v142, v142, v241, s[28:29]
	v_cndmask_b32_e64 v143, v143, v241, s[30:31]
	v_max3_f32 v246, v112, v113, v114
	v_max3_f32 v247, v115, v116, v117
	v_max3_f32 v246, v246, v118, v119
	v_max3_f32 v247, v247, v120, v121
	v_max3_f32 v246, v246, v122, v123
	ds_read_b64_tr_b16 v[100:101], v243 offset:52224
	ds_read_b64_tr_b16 v[102:103], v243 offset:52736
	v_mfma_f32_32x32x16_bf16 v[16:31], v[172:175], v[104:107], v[16:31]
	v_max3_f32 v247, v247, v124, v125
	v_max3_f32 v246, v246, v126, v127
	v_max3_f32 v247, v247, v128, v129
	v_max3_f32 v246, v246, v130, v131
	v_max3_f32 v247, v247, v132, v133
	v_max3_f32 v246, v246, v134, v135
	v_max3_f32 v247, v247, v136, v137
	v_max3_f32 v246, v246, v138, v139
	v_max3_f32 v247, v247, v140, v141
	v_max3_f32 v246, v246, v142, v143
	ds_read_b64_tr_b16 v[104:105], v243 offset:56320
	ds_read_b64_tr_b16 v[106:107], v243 offset:56832
	s_waitcnt lgkmcnt(8)
	v_mfma_f32_32x32x16_bf16 v[32:47], v[160:163], v[214:217], v[32:47]
	v_max_f32_e32 v248, v246, v247
	v_cmp_lt_f32_e32 vcc, s87, v248
	s_cbranch_vccnz .Lat_rare_T1

.Lat_rare_M1:
	v_mov_b32_e32 v246, v248
	s_nop 1
	v_permlane32_swap_b32_e32 v248, v246
	v_max_f32_e32 v248, v248, v246
	v_max_f32_e32 v249, 0, v248
	v_exp_f32_e64 v250, -v249
	v_add_f32_e32 v210, v210, v249
	v_xor_b32_e32 v64, 0x80000000, v210
	v_mov_b32_e32 v65, v64
	v_mov_b32_e32 v66, v64
	v_mov_b32_e32 v67, v64
	v_mov_b32_e32 v68, v64
	v_mov_b32_e32 v69, v64
	v_mov_b32_e32 v70, v64
	v_mov_b32_e32 v71, v64
	v_mov_b32_e32 v72, v64
	v_mov_b32_e32 v73, v64
	v_mov_b32_e32 v74, v64
	v_mov_b32_e32 v75, v64
	v_mov_b32_e32 v76, v64
	v_mov_b32_e32 v77, v64
	v_mov_b32_e32 v78, v64
	v_mov_b32_e32 v79, v64
	ds_write_b32 v226, v250
	v_sub_f32_e32 v112, v112, v249
	v_sub_f32_e32 v113, v113, v249
	v_sub_f32_e32 v114, v114, v249
	v_sub_f32_e32 v115, v115, v249
	v_sub_f32_e32 v116, v116, v249
	v_sub_f32_e32 v117, v117, v249
	v_sub_f32_e32 v118, v118, v249
	v_sub_f32_e32 v119, v119, v249
	v_sub_f32_e32 v120, v120, v249
	v_sub_f32_e32 v121, v121, v249
	v_sub_f32_e32 v122, v122, v249
	v_sub_f32_e32 v123, v123, v249
	v_sub_f32_e32 v124, v124, v249
	v_sub_f32_e32 v125, v125, v249
	v_sub_f32_e32 v126, v126, v249
	v_sub_f32_e32 v127, v127, v249
	v_sub_f32_e32 v128, v128, v249
	v_sub_f32_e32 v129, v129, v249
	v_sub_f32_e32 v130, v130, v249
	v_sub_f32_e32 v131, v131, v249
	v_sub_f32_e32 v132, v132, v249
	v_sub_f32_e32 v133, v133, v249
	v_sub_f32_e32 v134, v134, v249
	v_sub_f32_e32 v135, v135, v249
	v_sub_f32_e32 v136, v136, v249
	v_sub_f32_e32 v137, v137, v249
	v_sub_f32_e32 v138, v138, v249
	v_sub_f32_e32 v139, v139, v249
	v_sub_f32_e32 v140, v140, v249
	v_sub_f32_e32 v141, v141, v249
	v_sub_f32_e32 v142, v142, v249
	v_sub_f32_e32 v143, v143, v249
	v_mul_f32_e32 v211, v211, v250
	s_branch .Lat_cont_M1
.Lat_rare_M2:
	v_mov_b32_e32 v246, v248
	s_nop 1
	v_permlane32_swap_b32_e32 v248, v246
	v_max_f32_e32 v248, v248, v246
	v_max_f32_e32 v249, 0, v248
	v_exp_f32_e64 v250, -v249
	v_add_f32_e32 v210, v210, v249
	v_xor_b32_e32 v64, 0x80000000, v210
	v_mov_b32_e32 v65, v64
	v_mov_b32_e32 v66, v64
	v_mov_b32_e32 v67, v64
	v_mov_b32_e32 v68, v64
	v_mov_b32_e32 v69, v64
	v_mov_b32_e32 v70, v64
	v_mov_b32_e32 v71, v64
	v_mov_b32_e32 v72, v64
	v_mov_b32_e32 v73, v64
	v_mov_b32_e32 v74, v64
	v_mov_b32_e32 v75, v64
	v_mov_b32_e32 v76, v64
	v_mov_b32_e32 v77, v64
	v_mov_b32_e32 v78, v64
	v_mov_b32_e32 v79, v64
	ds_write_b32 v226, v250
	v_sub_f32_e32 v80, v80, v249
	v_sub_f32_e32 v81, v81, v249
	v_sub_f32_e32 v82, v82, v249
	v_sub_f32_e32 v83, v83, v249
	v_sub_f32_e32 v84, v84, v249
	v_sub_f32_e32 v85, v85, v249
	v_sub_f32_e32 v86, v86, v249
	v_sub_f32_e32 v87, v87, v249
	v_sub_f32_e32 v88, v88, v249
	v_sub_f32_e32 v89, v89, v249
	v_sub_f32_e32 v90, v90, v249
	v_sub_f32_e32 v91, v91, v249
	v_sub_f32_e32 v92, v92, v249
	v_sub_f32_e32 v93, v93, v249
	v_sub_f32_e32 v94, v94, v249
	v_sub_f32_e32 v95, v95, v249
	v_sub_f32_e32 v96, v96, v249
	v_sub_f32_e32 v97, v97, v249
	v_sub_f32_e32 v98, v98, v249
	v_sub_f32_e32 v99, v99, v249
	v_sub_f32_e32 v100, v100, v249
	v_sub_f32_e32 v101, v101, v249
	v_sub_f32_e32 v102, v102, v249
	v_sub_f32_e32 v103, v103, v249
	v_sub_f32_e32 v104, v104, v249
	v_sub_f32_e32 v105, v105, v249
	v_sub_f32_e32 v106, v106, v249
	v_sub_f32_e32 v107, v107, v249
	v_sub_f32_e32 v108, v108, v249
	v_sub_f32_e32 v109, v109, v249
	v_sub_f32_e32 v110, v110, v249
	v_sub_f32_e32 v111, v111, v249
	v_mul_f32_e32 v211, v211, v250
	s_branch .Lat_cont_M2
